# v94 + cost-weighted re-spacing: the 32 row-sum adds of the diff PV blocks moved (same order) out of the transcendental-heavy MFMA gaps into the later, empty gaps
# baseline (speedup 1.0000x reference)
; __device__ __forceinline__ unsigned cvtpk(float lo, float hi) { f32x2 v = {lo, hi}; bf16x2_t b = __builtin_convertvector(v, bf16x2_t); return __builtin_bit_cast(unsigned, b); }
; #define LAS __attribute__((address_space(3)))
; template <int MODE, int NDG> ...
;     ...
;         float s0 = 0.f, s1 = 0.f;
; #pragma unroll
;         for (int r = 0; r < 16; ++r) { p0[r] = __builtin_amdgcn_exp2f(p0[r]); p1[r] = __builtin_amdgcn_exp2f(p1[r]); s0 += p0[r]; s1 += p1[r]; }
;         l += s0 + s1;
;         pw[0] = (u32x4){cvtpk(p0[0], p0[1]), cvtpk(p0[2], p0[3]), cvtpk(p0[4], p0[5]), cvtpk(p0[6], p0[7])};
;         pw[1] = (u32x4){cvtpk(p0[8], p0[9]), cvtpk(p0[10], p0[11]), cvtpk(p0[12], p0[13]), cvtpk(p0[14], p0[15])};
;         pw[2] = (u32x4){cvtpk(p1[0], p1[1]), cvtpk(p1[2], p1[3]), cvtpk(p1[4], p1[5]), cvtpk(p1[6], p1[7])};
;         pw[3] = (u32x4){cvtpk(p1[8], p1[9]), cvtpk(p1[10], p1[11]), cvtpk(p1[12], p1[13]), cvtpk(p1[14], p1[15])};
;     }
;     LAS const unsigned char* vp = vst + ((lane >> 4) & 1) * 32 + (lane & 3) * 8 + (4 * hi + ((lane & 15) >> 2)) * 64;
; #pragma unroll
;     for (int ks = 0; ks < 4; ++ks)
; #pragma unroll
;         for (int dg = 0; dg < NDG; ++dg) {
;             const bf16x8 vf = vfrag(vp + dg * 4096 + ks * 1024);
;             o[dg] = __builtin_amdgcn_mfma_f32_32x32x16_bf16(vf, __builtin_bit_cast(bf16x8, pw[ks]), o[dg], 0, 0, 0);
;         }
.LBB0_197:
	v_add3_u32 v0, s54, v212, v181
	v_add3_u32 v194, v0, v213, v214
	v_exp_f32_e32 v1, v112
	v_exp_f32_e32 v5, v113
	v_exp_f32_e32 v7, v114
	v_exp_f32_e32 v9, v115
	v_exp_f32_e32 v11, v116
	v_exp_f32_e32 v13, v117
	ds_read_b64_tr_b16 v[114:115], v194 offset:53248
	ds_read_b64_tr_b16 v[116:117], v194 offset:53760
	v_exp_f32_e32 v113, v118
	v_exp_f32_e32 v15, v119
	v_cvt_pk_bf16_f32 v224, v1, v5
	v_cvt_pk_bf16_f32 v225, v7, v9
	v_cvt_pk_bf16_f32 v226, v11, v13
	v_cvt_pk_bf16_f32 v227, v113, v15
	ds_read_b64_tr_b16 v[228:229], v194 offset:54272
	ds_read_b64_tr_b16 v[230:231], v194 offset:54784
	s_waitcnt lgkmcnt(2)
	v_mfma_f32_32x32x16_bf16 v[64:79], v[114:117], v[224:227], v[64:79]
	ds_read_b64_tr_b16 v[114:115], v194 offset:57344
	ds_read_b64_tr_b16 v[116:117], v194 offset:57856
	ds_read_b64_tr_b16 v[232:233], v194 offset:58368
	ds_read_b64_tr_b16 v[234:235], v194 offset:58880
	v_add_u32_e32 v198, 0xd000, v194
	v_exp_f32_e32 v195, v120
	v_exp_f32_e32 v121, v121
	v_exp_f32_e32 v119, v122
	v_exp_f32_e32 v203, v125
	v_exp_f32_e32 v125, v126
	s_waitcnt lgkmcnt(2)
	v_mfma_f32_32x32x16_bf16 v[48:63], v[114:117], v[224:227], v[48:63]
	ds_read_b64_tr_b16 v[114:115], v194 offset:61440
	ds_read_b64_tr_b16 v[116:117], v194 offset:61952
	ds_read_b64_tr_b16 v[236:237], v198 offset:12288
	ds_read_b64_tr_b16 v[238:239], v198 offset:12800
	ds_read_b64_tr_b16 v[240:241], v194 offset:62464
	ds_read_b64_tr_b16 v[242:243], v194 offset:62976
	ds_read_b64_tr_b16 v[244:245], v198 offset:13312
	ds_read_b64_tr_b16 v[246:247], v198 offset:13824
	v_exp_f32_e32 v0, v96
	v_exp_f32_e32 v4, v97
	v_exp_f32_e32 v6, v98
	v_exp_f32_e32 v8, v99
	s_waitcnt lgkmcnt(6)
	v_mfma_f32_32x32x16_bf16 v[32:47], v[114:117], v[224:227], v[32:47]
	v_exp_f32_e32 v117, v123
	v_exp_f32_e32 v115, v124
	v_exp_f32_e32 v123, v127
	v_exp_f32_e32 v10, v100
	v_exp_f32_e32 v12, v101
	v_exp_f32_e32 v112, v102
	ds_read_b64_tr_b16 v[96:97], v194 offset:55296
	ds_read_b64_tr_b16 v[98:99], v194 offset:55808
	s_waitcnt lgkmcnt(6)
	v_mfma_f32_32x32x16_bf16 v[16:31], v[236:239], v[224:227], v[16:31]
	v_cvt_pk_bf16_f32 v224, v195, v121
	v_cvt_pk_bf16_f32 v225, v119, v117
	v_cvt_pk_bf16_f32 v226, v115, v203
	v_cvt_pk_bf16_f32 v227, v125, v123
	v_exp_f32_e32 v14, v103
	v_cvt_pk_bf16_f32 v100, v0, v4
	v_cvt_pk_bf16_f32 v101, v6, v8
	v_mfma_f32_32x32x16_bf16 v[64:79], v[228:231], v[224:227], v[64:79]
	v_cvt_pk_bf16_f32 v102, v10, v12
	v_cvt_pk_bf16_f32 v103, v112, v14
	v_exp_f32_e32 v120, v105
	v_exp_f32_e32 v118, v106
	v_mfma_f32_32x32x16_bf16 v[48:63], v[232:235], v[224:227], v[48:63]
	v_exp_f32_e32 v116, v107
	v_exp_f32_e32 v114, v108
	v_exp_f32_e32 v202, v109
	v_exp_f32_e32 v124, v110
	v_exp_f32_e32 v122, v111
	s_waitcnt lgkmcnt(4)
	v_mfma_f32_32x32x16_bf16 v[32:47], v[240:243], v[224:227], v[32:47]
	v_add_f32_e64 v0, v0, 0
	v_add_f32_e64 v1, v1, 0
	v_add_f32_e32 v0, v4, v0
	v_add_f32_e32 v1, v5, v1
	v_add_f32_e32 v0, v6, v0
	v_add_f32_e32 v1, v7, v1
	s_waitcnt lgkmcnt(2)
	v_mfma_f32_32x32x16_bf16 v[16:31], v[244:247], v[224:227], v[16:31]
	ds_read_b64_tr_b16 v[224:225], v194 offset:56320
	ds_read_b64_tr_b16 v[226:227], v194 offset:56832
	v_add_f32_e64 v0, v8, v0
	v_add_f32_e64 v1, v9, v1
	v_add_f32_e32 v0, v10, v0
	v_add_f32_e32 v1, v11, v1
	v_add_f32_e64 v0, v12, v0
	v_add_f32_e64 v1, v13, v1
	s_waitcnt lgkmcnt(2)
	v_mfma_f32_32x32x16_bf16 v[64:79], v[96:99], v[100:103], v[64:79]
	ds_read_b64_tr_b16 v[96:97], v194 offset:59392
	ds_read_b64_tr_b16 v[98:99], v194 offset:59904
	ds_read_b64_tr_b16 v[228:229], v194 offset:60416
	ds_read_b64_tr_b16 v[230:231], v194 offset:60928
	v_add_f32_e64 v0, v112, v0
	v_add_f32_e64 v1, v113, v1
	v_add_f32_e64 v0, v14, v0
	v_add_f32_e64 v1, v15, v1
	v_add_f32_e32 v1, v195, v1
	s_waitcnt lgkmcnt(2)
	v_mfma_f32_32x32x16_bf16 v[48:63], v[96:99], v[100:103], v[48:63]
	ds_read_b64_tr_b16 v[96:97], v194 offset:63488
	ds_read_b64_tr_b16 v[98:99], v194 offset:64000
	ds_read_b64_tr_b16 v[232:233], v198 offset:14336
	ds_read_b64_tr_b16 v[234:235], v198 offset:14848
	ds_read_b64_tr_b16 v[236:237], v194 offset:64512
	ds_read_b64_tr_b16 v[238:239], v194 offset:65024
	v_exp_f32_e32 v194, v104
	v_add_f32_e32 v1, v121, v1
	v_add_f32_e32 v0, v194, v0
	v_add_f32_e32 v0, v120, v0
	v_add_f32_e64 v0, v118, v0
	s_waitcnt lgkmcnt(4)
	v_mfma_f32_32x32x16_bf16 v[32:47], v[96:99], v[100:103], v[32:47]
	ds_read_b64_tr_b16 v[96:97], v198 offset:15360
	ds_read_b64_tr_b16 v[98:99], v198 offset:15872
	v_add_f32_e64 v1, v119, v1
	v_add_f32_e64 v0, v116, v0
	v_add_f32_e64 v1, v117, v1
	v_add_f32_e32 v0, v114, v0
	v_add_f32_e32 v1, v115, v1
	v_add_f32_e64 v0, v202, v0
	s_waitcnt lgkmcnt(4)
	v_mfma_f32_32x32x16_bf16 v[16:31], v[232:235], v[100:103], v[16:31]
	v_cvt_pk_bf16_f32 v100, v194, v120
	v_cvt_pk_bf16_f32 v101, v118, v116
	v_cvt_pk_bf16_f32 v102, v114, v202
	v_cvt_pk_bf16_f32 v103, v124, v122
	v_add_f32_e64 v1, v203, v1
	v_add_f32_e32 v0, v124, v0
	v_mfma_f32_32x32x16_bf16 v[64:79], v[224:227], v[100:103], v[64:79]
	v_add_f32_e32 v1, v125, v1
	v_add_f32_e64 v0, v122, v0
	v_add_f32_e64 v1, v123, v1
	v_add_f32_e32 v0, v0, v1
	v_add_f32_e32 v3, v3, v0
	v_mfma_f32_32x32x16_bf16 v[48:63], v[228:231], v[100:103], v[48:63]
	s_waitcnt lgkmcnt(2)
	v_mfma_f32_32x32x16_bf16 v[32:47], v[236:239], v[100:103], v[32:47]
	s_waitcnt lgkmcnt(0)
	v_mfma_f32_32x32x16_bf16 v[16:31], v[96:99], v[100:103], v[16:31]
	s_cmp_gt_u32 s50, s48
	s_cbranch_scc1 .LBB0_190

; __device__ __forceinline__ unsigned cvtpk(float lo, float hi) { f32x2 v = {lo, hi}; bf16x2_t b = __builtin_convertvector(v, bf16x2_t); return __builtin_bit_cast(unsigned, b); }
; #define LAS __attribute__((address_space(3)))
; template <int MODE, int NDG> ...
;     ...
;         float s0 = 0.f, s1 = 0.f;
; #pragma unroll
;         for (int r = 0; r < 16; ++r) { p0[r] = __builtin_amdgcn_exp2f(p0[r]); p1[r] = __builtin_amdgcn_exp2f(p1[r]); s0 += p0[r]; s1 += p1[r]; }
;         l += s0 + s1;
;         pw[0] = (u32x4){cvtpk(p0[0], p0[1]), cvtpk(p0[2], p0[3]), cvtpk(p0[4], p0[5]), cvtpk(p0[6], p0[7])};
;         pw[1] = (u32x4){cvtpk(p0[8], p0[9]), cvtpk(p0[10], p0[11]), cvtpk(p0[12], p0[13]), cvtpk(p0[14], p0[15])};
;         pw[2] = (u32x4){cvtpk(p1[0], p1[1]), cvtpk(p1[2], p1[3]), cvtpk(p1[4], p1[5]), cvtpk(p1[6], p1[7])};
;         pw[3] = (u32x4){cvtpk(p1[8], p1[9]), cvtpk(p1[10], p1[11]), cvtpk(p1[12], p1[13]), cvtpk(p1[14], p1[15])};
;     }
;     LAS const unsigned char* vp = vst + ((lane >> 4) & 1) * 32 + (lane & 3) * 8 + (4 * hi + ((lane & 15) >> 2)) * 64;
; #pragma unroll
;     for (int ks = 0; ks < 4; ++ks)
; #pragma unroll
;         for (int dg = 0; dg < NDG; ++dg) {
;             const bf16x8 vf = vfrag(vp + dg * 4096 + ks * 1024);
;             o[dg] = __builtin_amdgcn_mfma_f32_32x32x16_bf16(vf, __builtin_bit_cast(bf16x8, pw[ks]), o[dg], 0, 0, 0);
;         }
.LBB0_204:
	v_add3_u32 v0, s54, v212, v181
	v_add3_u32 v198, v0, v213, v214
	v_exp_f32_e32 v1, v112
	v_exp_f32_e32 v5, v113
	v_exp_f32_e32 v7, v114
	v_exp_f32_e32 v9, v115
	v_exp_f32_e32 v11, v116
	v_exp_f32_e32 v13, v117
	ds_read_b64_tr_b16 v[114:115], v198 offset:36864
	ds_read_b64_tr_b16 v[116:117], v198 offset:37376
	v_exp_f32_e32 v113, v118
	v_exp_f32_e32 v15, v119
	v_cvt_pk_bf16_f32 v222, v1, v5
	v_cvt_pk_bf16_f32 v223, v7, v9
	v_cvt_pk_bf16_f32 v224, v11, v13
	v_cvt_pk_bf16_f32 v225, v113, v15
	ds_read_b64_tr_b16 v[226:227], v198 offset:37888
	ds_read_b64_tr_b16 v[228:229], v198 offset:38400
	s_waitcnt lgkmcnt(2)
	v_mfma_f32_32x32x16_bf16 v[64:79], v[114:117], v[222:225], v[64:79]
	ds_read_b64_tr_b16 v[114:115], v198 offset:40960
	ds_read_b64_tr_b16 v[116:117], v198 offset:41472
	ds_read_b64_tr_b16 v[230:231], v198 offset:41984
	ds_read_b64_tr_b16 v[232:233], v198 offset:42496
	v_exp_f32_e32 v195, v120
	v_exp_f32_e32 v121, v121
	v_exp_f32_e32 v119, v122
	v_exp_f32_e32 v203, v125
	v_exp_f32_e32 v125, v126
	v_exp_f32_e32 v0, v96
	s_waitcnt lgkmcnt(2)
	v_mfma_f32_32x32x16_bf16 v[48:63], v[114:117], v[222:225], v[48:63]
	ds_read_b64_tr_b16 v[114:115], v198 offset:45056
	ds_read_b64_tr_b16 v[116:117], v198 offset:45568
	ds_read_b64_tr_b16 v[234:235], v198 offset:49152
	ds_read_b64_tr_b16 v[236:237], v198 offset:49664
	ds_read_b64_tr_b16 v[238:239], v198 offset:46080
	ds_read_b64_tr_b16 v[240:241], v198 offset:46592
	ds_read_b64_tr_b16 v[242:243], v198 offset:50176
	ds_read_b64_tr_b16 v[244:245], v198 offset:50688
	v_exp_f32_e32 v4, v97
	v_exp_f32_e32 v6, v98
	v_exp_f32_e32 v8, v99
	v_exp_f32_e32 v10, v100
	v_exp_f32_e32 v12, v101
	s_waitcnt lgkmcnt(6)
	v_mfma_f32_32x32x16_bf16 v[32:47], v[114:117], v[222:225], v[32:47]
	v_exp_f32_e32 v117, v123
	v_exp_f32_e32 v115, v124
	v_exp_f32_e32 v123, v127
	v_exp_f32_e32 v112, v102
	ds_read_b64_tr_b16 v[96:97], v198 offset:38912
	ds_read_b64_tr_b16 v[98:99], v198 offset:39424
	v_exp_f32_e32 v14, v103
	v_cvt_pk_bf16_f32 v100, v0, v4
	s_waitcnt lgkmcnt(6)
	v_mfma_f32_32x32x16_bf16 v[16:31], v[234:237], v[222:225], v[16:31]
	v_cvt_pk_bf16_f32 v222, v195, v121
	v_cvt_pk_bf16_f32 v223, v119, v117
	v_cvt_pk_bf16_f32 v224, v115, v203
	v_cvt_pk_bf16_f32 v225, v125, v123
	v_cvt_pk_bf16_f32 v101, v6, v8
	v_cvt_pk_bf16_f32 v102, v10, v12
	v_cvt_pk_bf16_f32 v103, v112, v14
	v_mfma_f32_32x32x16_bf16 v[64:79], v[226:229], v[222:225], v[64:79]
	v_exp_f32_e32 v194, v104
	v_exp_f32_e32 v120, v105
	v_exp_f32_e32 v118, v106
	v_mfma_f32_32x32x16_bf16 v[48:63], v[230:233], v[222:225], v[48:63]
	v_exp_f32_e32 v116, v107
	v_exp_f32_e32 v114, v108
	v_exp_f32_e32 v202, v109
	v_exp_f32_e32 v124, v110
	v_exp_f32_e32 v122, v111
	s_waitcnt lgkmcnt(4)
	v_mfma_f32_32x32x16_bf16 v[32:47], v[238:241], v[222:225], v[32:47]
	v_add_f32_e64 v0, v0, 0
	v_add_f32_e64 v1, v1, 0
	v_add_f32_e32 v0, v4, v0
	v_add_f32_e32 v1, v5, v1
	v_add_f32_e32 v0, v6, v0
	v_add_f32_e32 v1, v7, v1
	s_waitcnt lgkmcnt(2)
	v_mfma_f32_32x32x16_bf16 v[16:31], v[242:245], v[222:225], v[16:31]
	ds_read_b64_tr_b16 v[222:223], v198 offset:39936
	ds_read_b64_tr_b16 v[224:225], v198 offset:40448
	v_add_f32_e32 v0, v8, v0
	v_add_f32_e32 v1, v9, v1
	v_add_f32_e64 v0, v10, v0
	v_add_f32_e64 v1, v11, v1
	v_add_f32_e32 v0, v12, v0
	v_add_f32_e32 v1, v13, v1
	s_waitcnt lgkmcnt(2)
	v_mfma_f32_32x32x16_bf16 v[64:79], v[96:99], v[100:103], v[64:79]
	ds_read_b64_tr_b16 v[96:97], v198 offset:43008
	ds_read_b64_tr_b16 v[98:99], v198 offset:43520
	ds_read_b64_tr_b16 v[226:227], v198 offset:44032
	ds_read_b64_tr_b16 v[228:229], v198 offset:44544
	v_add_f32_e64 v0, v112, v0
	v_add_f32_e64 v1, v113, v1
	v_add_f32_e64 v0, v14, v0
	v_add_f32_e64 v1, v15, v1
	v_add_f32_e64 v0, v194, v0
	v_add_f32_e64 v1, v195, v1
	s_waitcnt lgkmcnt(2)
	v_mfma_f32_32x32x16_bf16 v[48:63], v[96:99], v[100:103], v[48:63]
	ds_read_b64_tr_b16 v[96:97], v198 offset:47104
	ds_read_b64_tr_b16 v[98:99], v198 offset:47616
	ds_read_b64_tr_b16 v[230:231], v198 offset:51200
	ds_read_b64_tr_b16 v[232:233], v198 offset:51712
	ds_read_b64_tr_b16 v[234:235], v198 offset:48128
	ds_read_b64_tr_b16 v[236:237], v198 offset:48640
	v_add_f32_e32 v0, v120, v0
	v_add_f32_e32 v1, v121, v1
	v_add_f32_e64 v0, v118, v0
	v_add_f32_e64 v1, v119, v1
	v_add_f32_e64 v0, v116, v0
	v_add_f32_e64 v1, v117, v1
	s_waitcnt lgkmcnt(4)
	v_mfma_f32_32x32x16_bf16 v[32:47], v[96:99], v[100:103], v[32:47]
	ds_read_b64_tr_b16 v[96:97], v198 offset:52224
	ds_read_b64_tr_b16 v[98:99], v198 offset:52736
	v_add_f32_e32 v0, v114, v0
	v_add_f32_e32 v1, v115, v1
	v_add_f32_e64 v0, v202, v0
	v_add_f32_e64 v1, v203, v1
	v_add_f32_e32 v0, v124, v0
	v_add_f32_e32 v1, v125, v1
	s_waitcnt lgkmcnt(4)
	v_mfma_f32_32x32x16_bf16 v[16:31], v[230:233], v[100:103], v[16:31]
	v_cvt_pk_bf16_f32 v100, v194, v120
	v_cvt_pk_bf16_f32 v101, v118, v116
	v_cvt_pk_bf16_f32 v102, v114, v202
	v_cvt_pk_bf16_f32 v103, v124, v122
	v_add_f32_e32 v0, v122, v0
	v_add_f32_e32 v1, v123, v1
	v_mfma_f32_32x32x16_bf16 v[64:79], v[222:225], v[100:103], v[64:79]
	v_add_f32_e32 v0, v0, v1
	v_add_f32_e32 v3, v3, v0
	v_mfma_f32_32x32x16_bf16 v[48:63], v[226:229], v[100:103], v[48:63]
	s_waitcnt lgkmcnt(2)
	v_mfma_f32_32x32x16_bf16 v[32:47], v[234:237], v[100:103], v[32:47]
	s_waitcnt lgkmcnt(0)
	v_mfma_f32_32x32x16_bf16 v[16:31], v[96:99], v[100:103], v[16:31]
	s_andn2_b64 vcc, exec, s[30:31]
	s_add_i32 s52, s52, 1
	s_cbranch_vccnz .LBB0_185
